# GEMM accumulator zeroing with v_mov_b64 (64 instead of 128 moves per tile) on top of P1 table unroll
# baseline (speedup 1.0000x reference)
; template <class Epi, class Sched, bool ALIGN_EPI = false, bool SP2 = false>
; __device__ __forceinline__ void gemm_phase(PG8_LAS unsigned char* lds, const Gemm g, const Sched& S, const Epi& E) {
;     ...
;         const bool has_next = S.next(ui + 1, nxt);
;         const char* nA = has_next ? (const char*)g.A + (size_t)nxt.pm * tstepA : cA; const char* nB = has_next ? (const char*)g.Bt + (size_t)nxt.pn * tstepB : cB;
;     ...
; #pragma unroll
;         for (int a = 0; a < 2; ++a)
; #pragma unroll
;             for (int b = 0; b < 2; ++b)
; #pragma unroll
;                 for (int m = 0; m < 4; ++m)
; #pragma unroll
;                     for (int n = 0; n < 2; ++n) acc[a][b][m][n] = (f32x4){0.f, 0.f, 0.f, 0.f};
.LBB0_237:
	s_ashr_i32 s45, s44, 31
	s_lshl_b64 s[50:51], s[44:45], 20
	s_add_u32 s50, s20, s50
	s_addc_u32 s51, s21, s51
	s_and_b64 s[52:53], s[38:39], exec
	s_cselect_b32 s45, s51, s63
	s_cselect_b32 s79, s50, s62
	s_ashr_i32 s41, s40, 31
	s_lshl_b64 s[52:53], s[40:41], 20
	s_add_u32 s52, s0, s52
	s_addc_u32 s53, s1, s53
	s_and_b64 s[66:67], s[38:39], exec
	s_cselect_b32 s41, s53, s65
	s_cselect_b32 s80, s52, s64
	s_add_u32 s62, s62, 0x80080
	s_addc_u32 s63, s63, 0
	s_add_u32 s81, s64, 0x100
	v_mov_b32_e32 v0, 0
	s_addc_u32 s82, s65, 0
	s_mov_b32 s83, -2
	v_mov_b32_e32 v1, v0
	v_mov_b64_e32 v[2:3], v[0:1]
	v_mov_b64_e32 v[4:5], v[0:1]
	v_mov_b64_e32 v[6:7], v[0:1]
	v_mov_b64_e32 v[8:9], v[0:1]
	v_mov_b64_e32 v[10:11], v[0:1]
	v_mov_b64_e32 v[12:13], v[0:1]
	v_mov_b64_e32 v[14:15], v[0:1]
	v_mov_b64_e32 v[16:17], v[0:1]
	v_mov_b64_e32 v[18:19], v[0:1]
	v_mov_b64_e32 v[20:21], v[0:1]
	v_mov_b64_e32 v[22:23], v[0:1]
	v_mov_b64_e32 v[24:25], v[0:1]
	v_mov_b64_e32 v[26:27], v[0:1]
	v_mov_b64_e32 v[28:29], v[0:1]
	v_mov_b64_e32 v[30:31], v[0:1]
	v_mov_b64_e32 v[32:33], v[0:1]
	v_mov_b64_e32 v[34:35], v[0:1]
	v_mov_b64_e32 v[36:37], v[0:1]
	v_mov_b64_e32 v[38:39], v[0:1]
	v_mov_b64_e32 v[40:41], v[0:1]
	v_mov_b64_e32 v[42:43], v[0:1]
	v_mov_b64_e32 v[44:45], v[0:1]
	v_mov_b64_e32 v[46:47], v[0:1]
	v_mov_b64_e32 v[48:49], v[0:1]
	v_mov_b64_e32 v[50:51], v[0:1]
	v_mov_b64_e32 v[52:53], v[0:1]
	v_mov_b64_e32 v[54:55], v[0:1]
	v_mov_b64_e32 v[56:57], v[0:1]
	v_mov_b64_e32 v[58:59], v[0:1]
	v_mov_b64_e32 v[60:61], v[0:1]
	v_mov_b64_e32 v[62:63], v[0:1]
	v_mov_b64_e32 v[64:65], v[0:1]
	v_mov_b64_e32 v[66:67], v[0:1]
	v_mov_b64_e32 v[68:69], v[0:1]
	v_mov_b64_e32 v[70:71], v[0:1]
	v_mov_b64_e32 v[72:73], v[0:1]
	v_mov_b64_e32 v[74:75], v[0:1]
	v_mov_b64_e32 v[76:77], v[0:1]
	v_mov_b64_e32 v[78:79], v[0:1]
	v_mov_b64_e32 v[80:81], v[0:1]
	v_mov_b64_e32 v[82:83], v[0:1]
	v_mov_b64_e32 v[84:85], v[0:1]
	v_mov_b64_e32 v[86:87], v[0:1]
	v_mov_b64_e32 v[88:89], v[0:1]
	v_mov_b64_e32 v[90:91], v[0:1]
	v_mov_b64_e32 v[92:93], v[0:1]
	v_mov_b64_e32 v[94:95], v[0:1]
	v_mov_b64_e32 v[96:97], v[0:1]
	v_mov_b64_e32 v[98:99], v[0:1]
	v_mov_b64_e32 v[100:101], v[0:1]
	v_mov_b64_e32 v[102:103], v[0:1]
	v_mov_b64_e32 v[104:105], v[0:1]
	v_mov_b64_e32 v[106:107], v[0:1]
	v_mov_b64_e32 v[108:109], v[0:1]
	v_mov_b64_e32 v[110:111], v[0:1]
	v_mov_b64_e32 v[112:113], v[0:1]
	v_mov_b64_e32 v[114:115], v[0:1]
	v_mov_b64_e32 v[116:117], v[0:1]
	v_mov_b64_e32 v[118:119], v[0:1]
	v_mov_b64_e32 v[120:121], v[0:1]
	v_mov_b64_e32 v[122:123], v[0:1]
	v_mov_b64_e32 v[124:125], v[0:1]
	v_mov_b64_e32 v[126:127], v[0:1]

; template <class Epi, class Sched, bool ALIGN_EPI = false, bool SP2 = false>
; __device__ __forceinline__ void gemm_phase(PG8_LAS unsigned char* lds, const Gemm g, const Sched& S, const Epi& E) {
;     ...
;         const bool has_next = S.next(ui + 1, nxt);
;         const char* nA = has_next ? (const char*)g.A + (size_t)nxt.pm * tstepA : cA; const char* nB = has_next ? (const char*)g.Bt + (size_t)nxt.pn * tstepB : cB;
;     ...
; #pragma unroll
;         for (int a = 0; a < 2; ++a)
; #pragma unroll
;             for (int b = 0; b < 2; ++b)
; #pragma unroll
;                 for (int m = 0; m < 4; ++m)
; #pragma unroll
;                     for (int n = 0; n < 2; ++n) acc[a][b][m][n] = (f32x4){0.f, 0.f, 0.f, 0.f};
.LBB0_363:
	s_ashr_i32 s69, s68, 31
	v_cmp_lt_i64_e32 vcc, s[40:41], v[142:143]
	s_lshl_b64 s[40:41], s[68:69], 18
	s_add_u32 s70, s43, s40
	s_addc_u32 s71, s62, s41
	s_and_b64 s[40:41], vcc, exec
	s_cselect_b32 s23, s71, s27
	s_cselect_b32 s52, s70, s26
	s_ashr_i32 s37, s36, 31
	s_lshl_b64 s[40:41], s[36:37], 18
	s_add_u32 s40, s34, s40
	s_addc_u32 s41, s35, s41
	s_and_b64 s[50:51], vcc, exec
	s_cselect_b32 s37, s41, s45
	s_cselect_b32 s53, s40, s44
	s_add_u32 s26, s26, 0x20080
	s_addc_u32 s27, s27, 0
	s_add_u32 s69, s44, 0x100
	v_mov_b32_e32 v0, 0
	s_addc_u32 s79, s45, 0
	s_mov_b32 s80, -2
	v_mov_b32_e32 v1, v0
	v_mov_b64_e32 v[2:3], v[0:1]
	v_mov_b64_e32 v[4:5], v[0:1]
	v_mov_b64_e32 v[6:7], v[0:1]
	v_mov_b64_e32 v[8:9], v[0:1]
	v_mov_b64_e32 v[10:11], v[0:1]
	v_mov_b64_e32 v[12:13], v[0:1]
	v_mov_b64_e32 v[14:15], v[0:1]
	v_mov_b64_e32 v[16:17], v[0:1]
	v_mov_b64_e32 v[18:19], v[0:1]
	v_mov_b64_e32 v[20:21], v[0:1]
	v_mov_b64_e32 v[22:23], v[0:1]
	v_mov_b64_e32 v[24:25], v[0:1]
	v_mov_b64_e32 v[26:27], v[0:1]
	v_mov_b64_e32 v[28:29], v[0:1]
	v_mov_b64_e32 v[30:31], v[0:1]
	v_mov_b64_e32 v[32:33], v[0:1]
	v_mov_b64_e32 v[34:35], v[0:1]
	v_mov_b64_e32 v[36:37], v[0:1]
	v_mov_b64_e32 v[38:39], v[0:1]
	v_mov_b64_e32 v[40:41], v[0:1]
	v_mov_b64_e32 v[42:43], v[0:1]
	v_mov_b64_e32 v[44:45], v[0:1]
	v_mov_b64_e32 v[46:47], v[0:1]
	v_mov_b64_e32 v[48:49], v[0:1]
	v_mov_b64_e32 v[50:51], v[0:1]
	v_mov_b64_e32 v[52:53], v[0:1]
	v_mov_b64_e32 v[54:55], v[0:1]
	v_mov_b64_e32 v[56:57], v[0:1]
	v_mov_b64_e32 v[58:59], v[0:1]
	v_mov_b64_e32 v[60:61], v[0:1]
	v_mov_b64_e32 v[62:63], v[0:1]
	v_mov_b64_e32 v[64:65], v[0:1]
	v_mov_b64_e32 v[66:67], v[0:1]
	v_mov_b64_e32 v[68:69], v[0:1]
	v_mov_b64_e32 v[70:71], v[0:1]
	v_mov_b64_e32 v[72:73], v[0:1]
	v_mov_b64_e32 v[74:75], v[0:1]
	v_mov_b64_e32 v[76:77], v[0:1]
	v_mov_b64_e32 v[78:79], v[0:1]
	v_mov_b64_e32 v[80:81], v[0:1]
	v_mov_b64_e32 v[82:83], v[0:1]
	v_mov_b64_e32 v[84:85], v[0:1]
	v_mov_b64_e32 v[86:87], v[0:1]
	v_mov_b64_e32 v[88:89], v[0:1]
	v_mov_b64_e32 v[90:91], v[0:1]
	v_mov_b64_e32 v[92:93], v[0:1]
	v_mov_b64_e32 v[94:95], v[0:1]
	v_mov_b64_e32 v[96:97], v[0:1]
	v_mov_b64_e32 v[98:99], v[0:1]
	v_mov_b64_e32 v[100:101], v[0:1]
	v_mov_b64_e32 v[102:103], v[0:1]
	v_mov_b64_e32 v[104:105], v[0:1]
	v_mov_b64_e32 v[106:107], v[0:1]
	v_mov_b64_e32 v[108:109], v[0:1]
	v_mov_b64_e32 v[110:111], v[0:1]
	v_mov_b64_e32 v[112:113], v[0:1]
	v_mov_b64_e32 v[114:115], v[0:1]
	v_mov_b64_e32 v[116:117], v[0:1]
	v_mov_b64_e32 v[118:119], v[0:1]
	v_mov_b64_e32 v[120:121], v[0:1]
	v_mov_b64_e32 v[122:123], v[0:1]
	v_mov_b64_e32 v[124:125], v[0:1]
	v_mov_b64_e32 v[126:127], v[0:1]

; template <class Epi, class Sched, bool ALIGN_EPI = false, bool SP2 = false>
; __device__ __forceinline__ void gemm_phase(PG8_LAS unsigned char* lds, const Gemm g, const Sched& S, const Epi& E) {
;     ...
;         const bool has_next = S.next(ui + 1, nxt);
;         const char* nA = has_next ? (const char*)g.A + (size_t)nxt.pm * tstepA : cA; const char* nB = has_next ? (const char*)g.Bt + (size_t)nxt.pn * tstepB : cB;
;     ...
; #pragma unroll
;         for (int a = 0; a < 2; ++a)
; #pragma unroll
;             for (int b = 0; b < 2; ++b)
; #pragma unroll
;                 for (int m = 0; m < 4; ++m)
; #pragma unroll
;                     for (int n = 0; n < 2; ++n) acc[a][b][m][n] = (f32x4){0.f, 0.f, 0.f, 0.f};
.LBB0_731:
	s_ashr_i32 s37, s36, 31
	s_lshl_b64 s[40:41], s[36:37], 20
	s_add_u32 s40, s20, s40
	s_addc_u32 s41, s21, s41
	s_and_b64 s[44:45], s[38:39], exec
	s_cselect_b32 s37, s41, s51
	s_cselect_b32 s71, s40, s50
	s_ashr_i32 s35, s34, 31
	s_lshl_b64 s[44:45], s[34:35], 20
	s_add_u32 s44, s88, s44
	s_addc_u32 s45, s89, s45
	s_and_b64 s[54:55], s[38:39], exec
	s_cselect_b32 s35, s45, s53
	s_cselect_b32 s74, s44, s52
	s_add_u32 s50, s50, 0x80080
	s_addc_u32 s51, s51, 0
	s_add_u32 s75, s52, 0x100
	v_mov_b32_e32 v0, 0
	s_addc_u32 s76, s53, 0
	s_mov_b32 s77, -2
	v_mov_b32_e32 v1, v0
	v_mov_b64_e32 v[2:3], v[0:1]
	v_mov_b64_e32 v[4:5], v[0:1]
	v_mov_b64_e32 v[6:7], v[0:1]
	v_mov_b64_e32 v[8:9], v[0:1]
	v_mov_b64_e32 v[10:11], v[0:1]
	v_mov_b64_e32 v[12:13], v[0:1]
	v_mov_b64_e32 v[14:15], v[0:1]
	v_mov_b64_e32 v[16:17], v[0:1]
	v_mov_b64_e32 v[18:19], v[0:1]
	v_mov_b64_e32 v[20:21], v[0:1]
	v_mov_b64_e32 v[22:23], v[0:1]
	v_mov_b64_e32 v[24:25], v[0:1]
	v_mov_b64_e32 v[26:27], v[0:1]
	v_mov_b64_e32 v[28:29], v[0:1]
	v_mov_b64_e32 v[30:31], v[0:1]
	v_mov_b64_e32 v[32:33], v[0:1]
	v_mov_b64_e32 v[34:35], v[0:1]
	v_mov_b64_e32 v[36:37], v[0:1]
	v_mov_b64_e32 v[38:39], v[0:1]
	v_mov_b64_e32 v[40:41], v[0:1]
	v_mov_b64_e32 v[42:43], v[0:1]
	v_mov_b64_e32 v[44:45], v[0:1]
	v_mov_b64_e32 v[46:47], v[0:1]
	v_mov_b64_e32 v[48:49], v[0:1]
	v_mov_b64_e32 v[50:51], v[0:1]
	v_mov_b64_e32 v[52:53], v[0:1]
	v_mov_b64_e32 v[54:55], v[0:1]
	v_mov_b64_e32 v[56:57], v[0:1]
	v_mov_b64_e32 v[58:59], v[0:1]
	v_mov_b64_e32 v[60:61], v[0:1]
	v_mov_b64_e32 v[62:63], v[0:1]
	v_mov_b64_e32 v[64:65], v[0:1]
	v_mov_b64_e32 v[66:67], v[0:1]
	v_mov_b64_e32 v[68:69], v[0:1]
	v_mov_b64_e32 v[70:71], v[0:1]
	v_mov_b64_e32 v[72:73], v[0:1]
	v_mov_b64_e32 v[74:75], v[0:1]
	v_mov_b64_e32 v[76:77], v[0:1]
	v_mov_b64_e32 v[78:79], v[0:1]
	v_mov_b64_e32 v[80:81], v[0:1]
	v_mov_b64_e32 v[82:83], v[0:1]
	v_mov_b64_e32 v[84:85], v[0:1]
	v_mov_b64_e32 v[86:87], v[0:1]
	v_mov_b64_e32 v[88:89], v[0:1]
	v_mov_b64_e32 v[90:91], v[0:1]
	v_mov_b64_e32 v[92:93], v[0:1]
	v_mov_b64_e32 v[94:95], v[0:1]
	v_mov_b64_e32 v[96:97], v[0:1]
	v_mov_b64_e32 v[98:99], v[0:1]
	v_mov_b64_e32 v[100:101], v[0:1]
	v_mov_b64_e32 v[102:103], v[0:1]
	v_mov_b64_e32 v[104:105], v[0:1]
	v_mov_b64_e32 v[106:107], v[0:1]
	v_mov_b64_e32 v[108:109], v[0:1]
	v_mov_b64_e32 v[110:111], v[0:1]
	v_mov_b64_e32 v[112:113], v[0:1]
	v_mov_b64_e32 v[114:115], v[0:1]
	v_mov_b64_e32 v[116:117], v[0:1]
	v_mov_b64_e32 v[118:119], v[0:1]
	v_mov_b64_e32 v[120:121], v[0:1]
	v_mov_b64_e32 v[122:123], v[0:1]
	v_mov_b64_e32 v[124:125], v[0:1]
	v_mov_b64_e32 v[126:127], v[0:1]

; template <class Epi, class Sched, bool ALIGN_EPI = false, bool SP2 = false>
; __device__ __forceinline__ void gemm_phase(PG8_LAS unsigned char* lds, const Gemm g, const Sched& S, const Epi& E) {
;     ...
;         const bool has_next = S.next(ui + 1, nxt);
;         const char* nA = has_next ? (const char*)g.A + (size_t)nxt.pm * tstepA : cA; const char* nB = has_next ? (const char*)g.Bt + (size_t)nxt.pn * tstepB : cB;
;     ...
; #pragma unroll
;         for (int a = 0; a < 2; ++a)
; #pragma unroll
;             for (int b = 0; b < 2; ++b)
; #pragma unroll
;                 for (int m = 0; m < 4; ++m)
; #pragma unroll
;                     for (int n = 0; n < 2; ++n) acc[a][b][m][n] = (f32x4){0.f, 0.f, 0.f, 0.f};
.LBB0_865:
	s_ashr_i32 s37, s36, 31
	s_lshl_b64 s[40:41], s[36:37], 20
	s_add_u32 s40, s20, s40
	s_addc_u32 s41, s21, s41
	s_and_b64 s[46:47], s[38:39], exec
	s_cselect_b32 s37, s41, s51
	s_cselect_b32 s71, s40, s50
	s_ashr_i32 s35, s34, 31
	s_lshl_b64 s[46:47], s[34:35], 20
	s_add_u32 s46, s84, s46
	s_addc_u32 s47, s85, s47
	s_and_b64 s[54:55], s[38:39], exec
	s_cselect_b32 s35, s47, s53
	s_cselect_b32 s72, s46, s52
	s_add_u32 s50, s50, 0x80080
	s_addc_u32 s51, s51, 0
	s_add_u32 s73, s52, 0x100
	v_mov_b32_e32 v0, 0
	s_addc_u32 s74, s53, 0
	s_mov_b32 s75, -2
	v_mov_b32_e32 v1, v0
	v_mov_b64_e32 v[2:3], v[0:1]
	v_mov_b64_e32 v[4:5], v[0:1]
	v_mov_b64_e32 v[6:7], v[0:1]
	v_mov_b64_e32 v[8:9], v[0:1]
	v_mov_b64_e32 v[10:11], v[0:1]
	v_mov_b64_e32 v[12:13], v[0:1]
	v_mov_b64_e32 v[14:15], v[0:1]
	v_mov_b64_e32 v[16:17], v[0:1]
	v_mov_b64_e32 v[18:19], v[0:1]
	v_mov_b64_e32 v[20:21], v[0:1]
	v_mov_b64_e32 v[22:23], v[0:1]
	v_mov_b64_e32 v[24:25], v[0:1]
	v_mov_b64_e32 v[26:27], v[0:1]
	v_mov_b64_e32 v[28:29], v[0:1]
	v_mov_b64_e32 v[30:31], v[0:1]
	v_mov_b64_e32 v[32:33], v[0:1]
	v_mov_b64_e32 v[34:35], v[0:1]
	v_mov_b64_e32 v[36:37], v[0:1]
	v_mov_b64_e32 v[38:39], v[0:1]
	v_mov_b64_e32 v[40:41], v[0:1]
	v_mov_b64_e32 v[42:43], v[0:1]
	v_mov_b64_e32 v[44:45], v[0:1]
	v_mov_b64_e32 v[46:47], v[0:1]
	v_mov_b64_e32 v[48:49], v[0:1]
	v_mov_b64_e32 v[50:51], v[0:1]
	v_mov_b64_e32 v[52:53], v[0:1]
	v_mov_b64_e32 v[54:55], v[0:1]
	v_mov_b64_e32 v[56:57], v[0:1]
	v_mov_b64_e32 v[58:59], v[0:1]
	v_mov_b64_e32 v[60:61], v[0:1]
	v_mov_b64_e32 v[62:63], v[0:1]
	v_mov_b64_e32 v[64:65], v[0:1]
	v_mov_b64_e32 v[66:67], v[0:1]
	v_mov_b64_e32 v[68:69], v[0:1]
	v_mov_b64_e32 v[70:71], v[0:1]
	v_mov_b64_e32 v[72:73], v[0:1]
	v_mov_b64_e32 v[74:75], v[0:1]
	v_mov_b64_e32 v[76:77], v[0:1]
	v_mov_b64_e32 v[78:79], v[0:1]
	v_mov_b64_e32 v[80:81], v[0:1]
	v_mov_b64_e32 v[82:83], v[0:1]
	v_mov_b64_e32 v[84:85], v[0:1]
	v_mov_b64_e32 v[86:87], v[0:1]
	v_mov_b64_e32 v[88:89], v[0:1]
	v_mov_b64_e32 v[90:91], v[0:1]
	v_mov_b64_e32 v[92:93], v[0:1]
	v_mov_b64_e32 v[94:95], v[0:1]
	v_mov_b64_e32 v[96:97], v[0:1]
	v_mov_b64_e32 v[98:99], v[0:1]
	v_mov_b64_e32 v[100:101], v[0:1]
	v_mov_b64_e32 v[102:103], v[0:1]
	v_mov_b64_e32 v[104:105], v[0:1]
	v_mov_b64_e32 v[106:107], v[0:1]
	v_mov_b64_e32 v[108:109], v[0:1]
	v_mov_b64_e32 v[110:111], v[0:1]
	v_mov_b64_e32 v[112:113], v[0:1]
	v_mov_b64_e32 v[114:115], v[0:1]
	v_mov_b64_e32 v[116:117], v[0:1]
	v_mov_b64_e32 v[118:119], v[0:1]
	v_mov_b64_e32 v[120:121], v[0:1]
	v_mov_b64_e32 v[122:123], v[0:1]
	v_mov_b64_e32 v[124:125], v[0:1]
	v_mov_b64_e32 v[126:127], v[0:1]

; template <class Epi, class Sched, bool ALIGN_EPI = false, bool SP2 = false>
; __device__ __forceinline__ void gemm_phase(PG8_LAS unsigned char* lds, const Gemm g, const Sched& S, const Epi& E) {
;     ...
; #pragma unroll
;         for (int a = 0; a < 2; ++a)
; #pragma unroll
;             for (int b = 0; b < 2; ++b)
; #pragma unroll
;                 for (int m = 0; m < 4; ++m)
; #pragma unroll
;                     for (int n = 0; n < 2; ++n) acc[a][b][m][n] = (f32x4){0.f, 0.f, 0.f, 0.f};
.LBB0_945:
	s_add_u32 s65, s36, 0x100
	v_mov_b32_e32 v0, 0
	s_addc_u32 s66, s37, 0
	s_mov_b32 s67, -2
	v_mov_b32_e32 v1, v0
	v_mov_b64_e32 v[2:3], v[0:1]
	v_mov_b64_e32 v[4:5], v[0:1]
	v_mov_b64_e32 v[6:7], v[0:1]
	v_mov_b64_e32 v[8:9], v[0:1]
	v_mov_b64_e32 v[10:11], v[0:1]
	v_mov_b64_e32 v[12:13], v[0:1]
	v_mov_b64_e32 v[14:15], v[0:1]
	v_mov_b64_e32 v[16:17], v[0:1]
	v_mov_b64_e32 v[18:19], v[0:1]
	v_mov_b64_e32 v[20:21], v[0:1]
	v_mov_b64_e32 v[22:23], v[0:1]
	v_mov_b64_e32 v[24:25], v[0:1]
	v_mov_b64_e32 v[26:27], v[0:1]
	v_mov_b64_e32 v[28:29], v[0:1]
	v_mov_b64_e32 v[30:31], v[0:1]
	v_mov_b64_e32 v[32:33], v[0:1]
	v_mov_b64_e32 v[34:35], v[0:1]
	v_mov_b64_e32 v[36:37], v[0:1]
	v_mov_b64_e32 v[38:39], v[0:1]
	v_mov_b64_e32 v[40:41], v[0:1]
	v_mov_b64_e32 v[42:43], v[0:1]
	v_mov_b64_e32 v[44:45], v[0:1]
	v_mov_b64_e32 v[46:47], v[0:1]
	v_mov_b64_e32 v[48:49], v[0:1]
	v_mov_b64_e32 v[50:51], v[0:1]
	v_mov_b64_e32 v[52:53], v[0:1]
	v_mov_b64_e32 v[54:55], v[0:1]
	v_mov_b64_e32 v[56:57], v[0:1]
	v_mov_b64_e32 v[58:59], v[0:1]
	v_mov_b64_e32 v[60:61], v[0:1]
	v_mov_b64_e32 v[62:63], v[0:1]
	v_mov_b64_e32 v[64:65], v[0:1]
	v_mov_b64_e32 v[66:67], v[0:1]
	v_mov_b64_e32 v[68:69], v[0:1]
	v_mov_b64_e32 v[70:71], v[0:1]
	v_mov_b64_e32 v[72:73], v[0:1]
	v_mov_b64_e32 v[74:75], v[0:1]
	v_mov_b64_e32 v[76:77], v[0:1]
	v_mov_b64_e32 v[78:79], v[0:1]
	v_mov_b64_e32 v[80:81], v[0:1]
	v_mov_b64_e32 v[82:83], v[0:1]
	v_mov_b64_e32 v[84:85], v[0:1]
	v_mov_b64_e32 v[86:87], v[0:1]
	v_mov_b64_e32 v[88:89], v[0:1]
	v_mov_b64_e32 v[90:91], v[0:1]
	v_mov_b64_e32 v[92:93], v[0:1]
	v_mov_b64_e32 v[94:95], v[0:1]
	v_mov_b64_e32 v[96:97], v[0:1]
	v_mov_b64_e32 v[98:99], v[0:1]
	v_mov_b64_e32 v[100:101], v[0:1]
	v_mov_b64_e32 v[102:103], v[0:1]
	v_mov_b64_e32 v[104:105], v[0:1]
	v_mov_b64_e32 v[106:107], v[0:1]
	v_mov_b64_e32 v[108:109], v[0:1]
	v_mov_b64_e32 v[110:111], v[0:1]
	v_mov_b64_e32 v[112:113], v[0:1]
	v_mov_b64_e32 v[114:115], v[0:1]
	v_mov_b64_e32 v[116:117], v[0:1]
	v_mov_b64_e32 v[118:119], v[0:1]
	v_mov_b64_e32 v[120:121], v[0:1]
	v_mov_b64_e32 v[122:123], v[0:1]
	v_mov_b64_e32 v[124:125], v[0:1]
	v_mov_b64_e32 v[126:127], v[0:1]
